# gla pass 1 k and v rows (read once) loaded with non-temporal loads
# baseline (speedup 1.0000x reference)
; template <bool OUT>
; __device__ __forceinline__ void gla_chunks(const Params& p, int l, const bf16_t* proj, LAS unsigned char* lds, int seg, int h, int dir, f32x4 (&Sacc)[4], float* outbuf, float& alog) {
;     ...
;         { u32x4 L0[8], L1[8]; bf16_t kr[8], qr[8];
; #pragma unroll
;           for (int j = 0; j < 8; ++j) { const int i = tb * 8 + j, t = dir ? t0 + 63 - i : t0 + i;
;               const u32x4* lr = (const u32x4*)(proj + (size_t)t * NP + GLR + dir * 16); L0[j] = lr[0]; L1[j] = lr[1];
;               kr[j] = proj[(size_t)t * NP + GK + h * 64 + d]; qr[j] = OUT ? proj[(size_t)t * NP + GQ + h * 64 + d] : (bf16_t)0; }
.LBB0_488:
	s_and_b64 s[22:23], s[4:5], exec
	s_cselect_b32 s22, s34, s33
	s_lshl_b32 s48, s22, 6
	s_add_i32 s48, s48, s35
	s_or_b32 s22, s48, 63
	s_sub_i32 s23, s22, s36
	s_add_i32 s49, s48, s36
	s_and_b64 s[50:51], s[4:5], exec
	s_cselect_b32 s23, s49, s23
	s_mul_hi_i32 s49, s23, 0x3800
	s_mulk_i32 s23, 0x3800
	s_add_u32 s54, s94, s23
	s_addc_u32 s49, s95, s49
	s_add_u32 s50, s54, s47
	s_addc_u32 s51, s49, 0
	s_add_u32 s52, s50, 0x3600
	s_addc_u32 s53, s51, 0
	s_lshl_b32 s23, s28, 1
	global_load_dwordx4 v[72:75], v189, s[52:53] offset:16
	global_load_dwordx4 v[76:79], v210, s[50:51] offset:1536
	s_add_u32 s50, s54, s23
	s_addc_u32 s51, s49, 0
	s_sub_i32 s49, s22, s40
	s_add_i32 s52, s48, s40
	v_lshl_add_u64 v[16:17], s[50:51], 0, v[188:189]
	s_and_b64 s[50:51], s[4:5], exec
	s_cselect_b32 s49, s52, s49
	s_mul_hi_i32 s50, s49, 0x3800
	s_mulk_i32 s49, 0x3800
	s_add_u32 s49, s94, s49
	s_addc_u32 s54, s95, s50
	s_add_u32 s50, s49, s47
	s_addc_u32 s51, s54, 0
	v_add_co_u32_e32 v16, vcc, s92, v16
	s_add_u32 s52, s50, 0x3600
	s_nop 0
	v_addc_co_u32_e32 v17, vcc, 0, v17, vcc
	s_addc_u32 s53, s51, 0
	global_load_ushort v109, v[16:17], off offset:3072 nt
	global_load_dwordx4 v[64:67], v189, s[52:53] offset:16
	global_load_dwordx4 v[68:71], v210, s[50:51] offset:1536
	s_add_u32 s50, s49, s23
	s_addc_u32 s51, s54, 0
	s_sub_i32 s49, s22, s41
	s_add_i32 s52, s48, s41
	v_lshl_add_u64 v[16:17], s[50:51], 0, v[188:189]
	s_and_b64 s[50:51], s[4:5], exec
	s_cselect_b32 s49, s52, s49
	s_mul_hi_i32 s50, s49, 0x3800
	s_mulk_i32 s49, 0x3800
	s_add_u32 s49, s94, s49
	s_addc_u32 s54, s95, s50
	s_add_u32 s50, s49, s47
	s_addc_u32 s51, s54, 0
	v_add_co_u32_e32 v16, vcc, s92, v16
	s_add_u32 s52, s50, 0x3600
	s_nop 0
	v_addc_co_u32_e32 v17, vcc, 0, v17, vcc
	s_addc_u32 s53, s51, 0
	global_load_ushort v110, v[16:17], off offset:3072 nt
	global_load_dwordx4 v[56:59], v189, s[52:53] offset:16
	global_load_dwordx4 v[60:63], v210, s[50:51] offset:1536
	s_add_u32 s50, s49, s23
	s_addc_u32 s51, s54, 0
	s_sub_i32 s49, s22, s42
	s_add_i32 s52, s48, s42
	v_lshl_add_u64 v[16:17], s[50:51], 0, v[188:189]
	s_and_b64 s[50:51], s[4:5], exec
	s_cselect_b32 s49, s52, s49
	s_mul_hi_i32 s50, s49, 0x3800
	s_mulk_i32 s49, 0x3800
	s_add_u32 s49, s94, s49
	s_addc_u32 s54, s95, s50
	s_add_u32 s50, s49, s47
	s_addc_u32 s51, s54, 0
	v_add_co_u32_e32 v16, vcc, s92, v16
	s_add_u32 s52, s50, 0x3600
	s_nop 0
	v_addc_co_u32_e32 v17, vcc, 0, v17, vcc
	s_addc_u32 s53, s51, 0
	global_load_ushort v111, v[16:17], off offset:3072 nt
	global_load_dwordx4 v[48:51], v189, s[52:53] offset:16
	global_load_dwordx4 v[52:55], v210, s[50:51] offset:1536
	s_add_u32 s50, s49, s23
	s_addc_u32 s51, s54, 0
	s_sub_i32 s49, s22, s43
	s_add_i32 s52, s48, s43
	v_lshl_add_u64 v[16:17], s[50:51], 0, v[188:189]
	s_and_b64 s[50:51], s[4:5], exec
	s_cselect_b32 s49, s52, s49
	s_mul_hi_i32 s50, s49, 0x3800
	s_mulk_i32 s49, 0x3800
	s_add_u32 s49, s94, s49
	s_addc_u32 s54, s95, s50
	s_add_u32 s50, s49, s47
	s_addc_u32 s51, s54, 0
	v_add_co_u32_e32 v16, vcc, s92, v16
	s_add_u32 s52, s50, 0x3600
	s_nop 0
	v_addc_co_u32_e32 v17, vcc, 0, v17, vcc
	s_addc_u32 s53, s51, 0
	global_load_ushort v112, v[16:17], off offset:3072 nt
	global_load_dwordx4 v[40:43], v189, s[52:53] offset:16
	global_load_dwordx4 v[44:47], v210, s[50:51] offset:1536
	s_add_u32 s50, s49, s23
	s_addc_u32 s51, s54, 0
	s_sub_i32 s49, s22, s44
	s_add_i32 s52, s48, s44
	v_lshl_add_u64 v[16:17], s[50:51], 0, v[188:189]
	s_and_b64 s[50:51], s[4:5], exec
	s_cselect_b32 s49, s52, s49
	s_mul_hi_i32 s50, s49, 0x3800
	s_mulk_i32 s49, 0x3800
	s_add_u32 s49, s94, s49
	s_addc_u32 s54, s95, s50
	s_add_u32 s50, s49, s47
	s_addc_u32 s51, s54, 0
	v_add_co_u32_e32 v16, vcc, s92, v16
	s_add_u32 s52, s50, 0x3600
	s_nop 0
	v_addc_co_u32_e32 v17, vcc, 0, v17, vcc
	s_addc_u32 s53, s51, 0
	global_load_ushort v113, v[16:17], off offset:3072 nt
	global_load_dwordx4 v[32:35], v189, s[52:53] offset:16
	global_load_dwordx4 v[36:39], v210, s[50:51] offset:1536
	s_add_u32 s50, s49, s23
	s_addc_u32 s51, s54, 0
	s_sub_i32 s49, s22, s45
	s_add_i32 s52, s48, s45
	v_lshl_add_u64 v[16:17], s[50:51], 0, v[188:189]
	s_and_b64 s[50:51], s[4:5], exec
	s_cselect_b32 s49, s52, s49
	s_mul_hi_i32 s50, s49, 0x3800
	s_mulk_i32 s49, 0x3800
	s_add_u32 s49, s94, s49
	s_addc_u32 s54, s95, s50
	s_add_u32 s50, s49, s47
	s_addc_u32 s51, s54, 0
	v_add_co_u32_e32 v16, vcc, s92, v16
	s_add_u32 s52, s50, 0x3600
	s_nop 0
	v_addc_co_u32_e32 v17, vcc, 0, v17, vcc
	s_addc_u32 s53, s51, 0
	global_load_ushort v114, v[16:17], off offset:3072 nt
	global_load_dwordx4 v[24:27], v189, s[52:53] offset:16
	global_load_dwordx4 v[28:31], v210, s[50:51] offset:1536
	s_add_u32 s50, s49, s23
	s_addc_u32 s51, s54, 0
	s_sub_i32 s22, s22, s46
	s_add_i32 s49, s48, s46
	v_lshl_add_u64 v[16:17], s[50:51], 0, v[188:189]
	s_and_b64 s[50:51], s[4:5], exec
	s_cselect_b32 s22, s49, s22
	s_mul_hi_i32 s49, s22, 0x3800
	s_mulk_i32 s22, 0x3800
	s_add_u32 s22, s94, s22
	s_addc_u32 s49, s95, s49
	s_add_u32 s50, s22, s47
	s_addc_u32 s51, s49, 0
	s_add_u32 s52, s50, 0x3600
	s_addc_u32 s53, s51, 0
	s_add_u32 s22, s22, s23
	v_add_co_u32_e32 v16, vcc, s92, v16
	s_addc_u32 s23, s49, 0
	s_nop 0
	v_addc_co_u32_e32 v17, vcc, 0, v17, vcc
	v_lshl_add_u64 v[116:117], s[22:23], 0, v[188:189]
	v_add_co_u32_e32 v116, vcc, s92, v116
	global_load_ushort v115, v[16:17], off offset:3072 nt
	s_nop 0
	v_addc_co_u32_e32 v117, vcc, 0, v117, vcc
	global_load_dwordx4 v[16:19], v189, s[52:53] offset:16
	global_load_dwordx4 v[20:23], v210, s[50:51] offset:1536
	s_nop 0
	global_load_ushort v116, v[116:117], off offset:3072 nt
	s_waitcnt vmcnt(22)
; __device__ __forceinline__ float bf_lo(unsigned w) { return __uint_as_float(w << 16); }
; __device__ __forceinline__ float bf_hi(unsigned w) { return __uint_as_float(w & 0xffff0000u); }
; template <bool OUT>
; __device__ __forceinline__ void gla_chunks(const Params& p, int l, const bf16_t* proj, LAS unsigned char* lds, int seg, int h, int dir, f32x4 (&Sacc)[4], float* outbuf, float& alog) {
;     ...
;           for (int j = 0; j < 8; ++j) { const u32x4 l0 = L0[j], l1 = L1[j]; float z = bias;
; #pragma unroll
;               for (int e = 0; e < 4; ++e) { z += bf_lo(l0[e]) * w[e * 2] + bf_hi(l0[e]) * w[e * 2 + 1]; z += bf_lo(l1[e]) * w[8 + e * 2] + bf_hi(l1[e]) * w[8 + e * 2 + 1]; }
;               const float ls = fminf(z, 0.f) - __logf(1.0f + __expf(-fabsf(z)));
	v_lshlrev_b32_e32 v85, 16, v76
	v_and_b32_e32 v76, 0xffff0000, v76
	v_mul_f32_e32 v76, v87, v76
	v_fmac_f32_e32 v76, v95, v85
	v_lshlrev_b32_e32 v85, 16, v72
	v_and_b32_e32 v72, 0xffff0000, v72
	v_mul_f32_e32 v72, v92, v72
	v_add_f32_e32 v76, v86, v76
	v_fmac_f32_e32 v72, v91, v85
	v_add_f32_e32 v72, v72, v76
	v_lshlrev_b32_e32 v76, 16, v77
	v_and_b32_e32 v77, 0xffff0000, v77
	v_mul_f32_e32 v77, v89, v77
	v_fmac_f32_e32 v77, v88, v76
	v_lshlrev_b32_e32 v76, 16, v73
	v_and_b32_e32 v73, 0xffff0000, v73
	v_mul_f32_e32 v73, v94, v73
	v_add_f32_e32 v72, v77, v72
	v_fmac_f32_e32 v73, v93, v76
	v_and_b32_e32 v76, 0xffff0000, v78
	v_add_f32_e32 v72, v73, v72
	v_lshlrev_b32_e32 v73, 16, v78
	v_mul_f32_e32 v76, v96, v76
	v_fmac_f32_e32 v76, v90, v73
	v_lshlrev_b32_e32 v73, 16, v74
	v_and_b32_e32 v74, 0xffff0000, v74
	v_mul_f32_e32 v74, v100, v74
	v_add_f32_e32 v72, v76, v72
	v_fmac_f32_e32 v74, v99, v73
	v_add_f32_e32 v72, v74, v72
	v_and_b32_e32 v74, 0xffff0000, v79
	v_lshlrev_b32_e32 v73, 16, v79
	v_mul_f32_e32 v74, v98, v74
	v_fmac_f32_e32 v74, v97, v73
	v_add_f32_e32 v72, v74, v72
	v_lshlrev_b32_e32 v73, 16, v75
	v_and_b32_e32 v74, 0xffff0000, v75
	s_waitcnt vmcnt(19)
	v_lshlrev_b32_e32 v75, 16, v68
	v_and_b32_e32 v68, 0xffff0000, v68
	v_mul_f32_e32 v68, v87, v68
	v_fmac_f32_e32 v68, v95, v75
	v_lshlrev_b32_e32 v75, 16, v64
	v_and_b32_e32 v64, 0xffff0000, v64
	v_mul_f32_e32 v64, v92, v64
	v_add_f32_e32 v68, v86, v68
	v_fmac_f32_e32 v64, v91, v75
	v_add_f32_e32 v64, v64, v68
	v_lshlrev_b32_e32 v68, 16, v69
	v_and_b32_e32 v69, 0xffff0000, v69
	v_mul_f32_e32 v69, v89, v69
	v_fmac_f32_e32 v69, v88, v68
	v_lshlrev_b32_e32 v68, 16, v65
	v_and_b32_e32 v65, 0xffff0000, v65
	v_mul_f32_e32 v65, v94, v65
	v_add_f32_e32 v64, v69, v64
	v_fmac_f32_e32 v65, v93, v68
	v_and_b32_e32 v68, 0xffff0000, v70
	v_add_f32_e32 v64, v65, v64
	v_lshlrev_b32_e32 v65, 16, v70
	v_mul_f32_e32 v68, v96, v68
	v_mul_f32_e32 v74, v102, v74
	v_fmac_f32_e32 v68, v90, v65
	v_fmac_f32_e32 v74, v101, v73
	v_add_f32_e32 v64, v68, v64
	s_waitcnt vmcnt(16)
	v_lshlrev_b32_e32 v68, 16, v60
	v_and_b32_e32 v60, 0xffff0000, v60
	v_add_f32_e32 v72, v74, v72
	v_mul_f32_e32 v60, v87, v60
	v_mul_f32_e64 v73, |v72|, s60
	v_fmac_f32_e32 v60, v95, v68
	v_lshlrev_b32_e32 v68, 16, v56
	v_and_b32_e32 v56, 0xffff0000, v56
	v_exp_f32_e32 v73, v73
	v_lshlrev_b32_e32 v65, 16, v66
	v_and_b32_e32 v66, 0xffff0000, v66
	v_mul_f32_e32 v56, v92, v56
	v_mul_f32_e32 v66, v100, v66
	v_add_f32_e32 v60, v86, v60
	v_fmac_f32_e32 v56, v91, v68
	v_fmac_f32_e32 v66, v99, v65
	v_add_f32_e32 v56, v56, v60
	v_lshlrev_b32_e32 v60, 16, v61
	v_and_b32_e32 v61, 0xffff0000, v61
	v_add_f32_e32 v64, v66, v64
	v_and_b32_e32 v66, 0xffff0000, v71
	v_mul_f32_e32 v61, v89, v61
	v_add_f32_e32 v73, 1.0, v73
	v_lshlrev_b32_e32 v65, 16, v71
	v_mul_f32_e32 v66, v98, v66
	v_fmac_f32_e32 v61, v88, v60
	v_lshlrev_b32_e32 v60, 16, v57
	v_and_b32_e32 v57, 0xffff0000, v57
	v_cmp_gt_f32_e32 vcc, s1, v73
	v_fmac_f32_e32 v66, v97, v65
	v_mul_f32_e32 v57, v94, v57
	v_cndmask_b32_e64 v74, 0, 32, vcc
	v_add_f32_e32 v64, v66, v64
	v_and_b32_e32 v66, 0xffff0000, v67
	v_add_f32_e32 v56, v61, v56
	v_fmac_f32_e32 v57, v93, v60
	v_and_b32_e32 v60, 0xffff0000, v62
	v_ldexp_f32 v73, v73, v74
	v_lshlrev_b32_e32 v65, 16, v67
	v_mul_f32_e32 v66, v102, v66
	v_add_f32_e32 v56, v57, v56
	v_lshlrev_b32_e32 v57, 16, v62
	v_mul_f32_e32 v60, v96, v60
	v_log_f32_e32 v73, v73
	v_fmac_f32_e32 v66, v101, v65
	v_fmac_f32_e32 v60, v90, v57
	v_add_f32_e32 v65, v66, v64
	v_add_f32_e32 v56, v60, v56
	s_waitcnt vmcnt(13)
	v_lshlrev_b32_e32 v60, 16, v52
	v_and_b32_e32 v52, 0xffff0000, v52
	v_mul_f32_e64 v64, |v65|, s60
	v_mul_f32_e32 v52, v87, v52
	v_exp_f32_e32 v64, v64
	v_lshlrev_b32_e32 v57, 16, v58
	v_and_b32_e32 v58, 0xffff0000, v58
	v_fmac_f32_e32 v52, v95, v60
	v_lshlrev_b32_e32 v60, 16, v48
	v_and_b32_e32 v48, 0xffff0000, v48
	v_mul_f32_e32 v74, 0x3f317217, v73
	v_mul_f32_e32 v58, v100, v58
	v_mul_f32_e32 v48, v92, v48
	v_fma_f32 v74, v73, s74, -v74
	v_fmac_f32_e32 v58, v99, v57
	v_add_f32_e32 v52, v86, v52
	v_fmac_f32_e32 v48, v91, v60
	v_fmac_f32_e32 v74, 0x3377d1cf, v73
	v_add_f32_e32 v56, v58, v56
	v_and_b32_e32 v58, 0xffff0000, v63
	v_add_f32_e32 v48, v48, v52
	v_lshlrev_b32_e32 v52, 16, v53
	v_and_b32_e32 v53, 0xffff0000, v53
	v_fmac_f32_e32 v74, 0x3f317217, v73
	v_cmp_lt_f32_e64 s[22:23], |v73|, s70
	v_add_f32_e32 v64, 1.0, v64
	v_lshlrev_b32_e32 v57, 16, v63
	v_mul_f32_e32 v58, v98, v58
	v_mul_f32_e32 v53, v89, v53
	v_cndmask_b32_e64 v66, v73, v74, s[22:23]
	v_cndmask_b32_e32 v67, 0, v214, vcc
	v_cmp_gt_f32_e32 vcc, s1, v64
	v_fmac_f32_e32 v58, v97, v57
	v_fmac_f32_e32 v53, v88, v52
	v_lshlrev_b32_e32 v52, 16, v49
	v_and_b32_e32 v49, 0xffff0000, v49
	v_sub_f32_e32 v66, v66, v67
	v_cndmask_b32_e64 v67, 0, 32, vcc
	v_add_f32_e32 v56, v58, v56
	v_and_b32_e32 v58, 0xffff0000, v59
	v_mul_f32_e32 v49, v94, v49
	v_ldexp_f32 v64, v64, v67
	v_lshlrev_b32_e32 v57, 16, v59
	v_mul_f32_e32 v58, v102, v58
	v_add_f32_e32 v48, v53, v48
	v_fmac_f32_e32 v49, v93, v52
	v_and_b32_e32 v52, 0xffff0000, v54
	v_log_f32_e32 v67, v64
	v_fmac_f32_e32 v58, v101, v57
	v_add_f32_e32 v48, v49, v48
	v_lshlrev_b32_e32 v49, 16, v54
	v_mul_f32_e32 v52, v96, v52
	v_add_f32_e32 v57, v58, v56
	v_fmac_f32_e32 v52, v90, v49
	v_mul_f32_e64 v56, |v57|, s60
	v_add_f32_e32 v48, v52, v48
	s_waitcnt vmcnt(10)
; __device__ __forceinline__ float bf_lo(unsigned w) { return __uint_as_float(w << 16); }
; __device__ __forceinline__ float bf_hi(unsigned w) { return __uint_as_float(w & 0xffff0000u); }
; template <bool OUT>
; __device__ __forceinline__ void gla_chunks(const Params& p, int l, const bf16_t* proj, LAS unsigned char* lds, int seg, int h, int dir, f32x4 (&Sacc)[4], float* outbuf, float& alog) {
;     ...
;           for (int j = 0; j < 8; ++j) { const u32x4 l0 = L0[j], l1 = L1[j]; float z = bias;
; #pragma unroll
;               for (int e = 0; e < 4; ++e) { z += bf_lo(l0[e]) * w[e * 2] + bf_hi(l0[e]) * w[e * 2 + 1]; z += bf_lo(l1[e]) * w[8 + e * 2] + bf_hi(l1[e]) * w[8 + e * 2 + 1]; }
;               const float ls = fminf(z, 0.f) - __logf(1.0f + __expf(-fabsf(z)));
;               run += ls * (1.0f / 16.0f); bq[j] = run;
	v_lshlrev_b32_e32 v52, 16, v44
	v_and_b32_e32 v44, 0xffff0000, v44
	v_min_f32_e32 v72, 0, v72
	v_exp_f32_e32 v56, v56
	v_lshlrev_b32_e32 v49, 16, v50
	v_and_b32_e32 v50, 0xffff0000, v50
	v_mul_f32_e32 v44, v87, v44
	v_sub_f32_e32 v64, v72, v66
	v_mul_f32_e32 v66, 0x3f317217, v67
	v_mul_f32_e32 v50, v100, v50
	v_fmac_f32_e32 v44, v95, v52
	v_lshlrev_b32_e32 v52, 16, v40
	v_and_b32_e32 v40, 0xffff0000, v40
	v_fma_f32 v66, v67, s74, -v66
	v_fmac_f32_e32 v50, v99, v49
	v_mul_f32_e32 v40, v92, v40
	v_fmac_f32_e32 v66, 0x3377d1cf, v67
	v_add_f32_e32 v48, v50, v48
	v_and_b32_e32 v50, 0xffff0000, v55
	v_add_f32_e32 v44, v86, v44
	v_fmac_f32_e32 v40, v91, v52
	v_fmac_f32_e32 v66, 0x3f317217, v67
	v_cmp_lt_f32_e64 s[22:23], |v67|, s70
	v_add_f32_e32 v56, 1.0, v56
	v_lshlrev_b32_e32 v49, 16, v55
	v_mul_f32_e32 v50, v98, v50
	v_add_f32_e32 v40, v40, v44
	v_lshlrev_b32_e32 v44, 16, v45
	v_and_b32_e32 v45, 0xffff0000, v45
	v_cndmask_b32_e64 v58, v67, v66, s[22:23]
	v_cndmask_b32_e32 v59, 0, v214, vcc
	v_cmp_gt_f32_e32 vcc, s1, v56
	v_fmac_f32_e32 v50, v97, v49
	v_mul_f32_e32 v45, v89, v45
	v_sub_f32_e32 v58, v58, v59
	v_cndmask_b32_e64 v59, 0, 32, vcc
	v_add_f32_e32 v48, v50, v48
	v_and_b32_e32 v50, 0xffff0000, v51
	v_fmac_f32_e32 v45, v88, v44
	v_lshlrev_b32_e32 v44, 16, v41
	v_and_b32_e32 v41, 0xffff0000, v41
	v_ldexp_f32 v56, v56, v59
	v_lshlrev_b32_e32 v49, 16, v51
	v_mul_f32_e32 v50, v102, v50
	v_mul_f32_e32 v41, v94, v41
	v_log_f32_e32 v59, v56
	v_fmac_f32_e32 v50, v101, v49
	v_add_f32_e32 v40, v45, v40
	v_fmac_f32_e32 v41, v93, v44
	v_and_b32_e32 v44, 0xffff0000, v46
	v_add_f32_e32 v49, v50, v48
	v_add_f32_e32 v40, v41, v40
	v_lshlrev_b32_e32 v41, 16, v46
	v_mul_f32_e32 v44, v96, v44
	v_mul_f32_e64 v48, |v49|, s60
	v_fmac_f32_e32 v44, v90, v41
	v_min_f32_e32 v65, 0, v65
	v_exp_f32_e32 v48, v48
	v_add_f32_e32 v40, v44, v40
	v_lshlrev_b32_e32 v41, 16, v42
	v_and_b32_e32 v42, 0xffff0000, v42
	s_waitcnt vmcnt(7)
	v_lshlrev_b32_e32 v44, 16, v36
	v_and_b32_e32 v36, 0xffff0000, v36
	v_sub_f32_e32 v56, v65, v58
	v_mul_f32_e32 v58, 0x3f317217, v59
	v_mul_f32_e32 v42, v100, v42
	v_mul_f32_e32 v36, v87, v36
	v_fma_f32 v58, v59, s74, -v58
	v_fmac_f32_e32 v42, v99, v41
	v_fmac_f32_e32 v36, v95, v44
	v_lshlrev_b32_e32 v44, 16, v32
	v_and_b32_e32 v32, 0xffff0000, v32
	v_fmac_f32_e32 v58, 0x3377d1cf, v59
	v_add_f32_e32 v40, v42, v40
	v_and_b32_e32 v42, 0xffff0000, v47
	v_mul_f32_e32 v32, v92, v32
	v_fmac_f32_e32 v58, 0x3f317217, v59
	v_cmp_lt_f32_e64 s[22:23], |v59|, s70
	v_add_f32_e32 v48, 1.0, v48
	v_lshlrev_b32_e32 v41, 16, v47
	v_mul_f32_e32 v42, v98, v42
	v_add_f32_e32 v36, v86, v36
	v_fmac_f32_e32 v32, v91, v44
	v_cndmask_b32_e64 v50, v59, v58, s[22:23]
	v_cndmask_b32_e32 v51, 0, v214, vcc
	v_cmp_gt_f32_e32 vcc, s1, v48
	v_fmac_f32_e32 v42, v97, v41
	v_add_f32_e32 v32, v32, v36
	v_lshlrev_b32_e32 v36, 16, v37
	v_and_b32_e32 v37, 0xffff0000, v37
	v_sub_f32_e32 v50, v50, v51
	v_cndmask_b32_e64 v51, 0, 32, vcc
	v_add_f32_e32 v40, v42, v40
	v_and_b32_e32 v42, 0xffff0000, v43
	v_mul_f32_e32 v37, v89, v37
	v_ldexp_f32 v48, v48, v51
	v_lshlrev_b32_e32 v41, 16, v43
	v_mul_f32_e32 v42, v102, v42
	v_fmac_f32_e32 v37, v88, v36
	v_lshlrev_b32_e32 v36, 16, v33
	v_and_b32_e32 v33, 0xffff0000, v33
	v_log_f32_e32 v51, v48
	v_fmac_f32_e32 v42, v101, v41
	v_mul_f32_e32 v33, v94, v33
	v_add_f32_e32 v41, v42, v40
	v_add_f32_e32 v32, v37, v32
	v_fmac_f32_e32 v33, v93, v36
	v_and_b32_e32 v36, 0xffff0000, v38
	v_mul_f32_e64 v40, |v41|, s60
	v_add_f32_e32 v32, v33, v32
	v_lshlrev_b32_e32 v33, 16, v38
	v_mul_f32_e32 v36, v96, v36
	v_min_f32_e32 v57, 0, v57
	v_exp_f32_e32 v40, v40
	v_fmac_f32_e32 v36, v90, v33
	v_lshlrev_b32_e32 v33, 16, v34
	v_and_b32_e32 v34, 0xffff0000, v34
	v_sub_f32_e32 v48, v57, v50
	v_mul_f32_e32 v50, 0x3f317217, v51
	v_mul_f32_e32 v34, v100, v34
	v_fma_f32 v50, v51, s74, -v50
	v_add_f32_e32 v32, v36, v32
	v_fmac_f32_e32 v34, v99, v33
	v_fmac_f32_e32 v50, 0x3377d1cf, v51
	v_add_f32_e32 v32, v34, v32
	v_and_b32_e32 v34, 0xffff0000, v39
	v_fmac_f32_e32 v50, 0x3f317217, v51
	v_cmp_lt_f32_e64 s[22:23], |v51|, s70
	v_add_f32_e32 v40, 1.0, v40
	v_lshlrev_b32_e32 v33, 16, v39
	v_mul_f32_e32 v34, v98, v34
	v_cndmask_b32_e64 v42, v51, v50, s[22:23]
	v_cndmask_b32_e32 v43, 0, v214, vcc
	v_cmp_gt_f32_e32 vcc, s1, v40
	v_fmac_f32_e32 v34, v97, v33
	v_sub_f32_e32 v42, v42, v43
	v_cndmask_b32_e64 v43, 0, 32, vcc
	v_add_f32_e32 v32, v34, v32
	v_and_b32_e32 v34, 0xffff0000, v35
	v_ldexp_f32 v40, v40, v43
	v_lshlrev_b32_e32 v33, 16, v35
	v_mul_f32_e32 v34, v102, v34
	v_log_f32_e32 v43, v40
	v_fmac_f32_e32 v34, v101, v33
	v_add_f32_e32 v33, v34, v32
	v_mul_f32_e64 v32, |v33|, s60
	v_min_f32_e32 v49, 0, v49
	v_exp_f32_e32 v32, v32
	v_sub_f32_e32 v40, v49, v42
	v_mul_f32_e32 v42, 0x3f317217, v43
	v_fma_f32 v42, v43, s74, -v42
	v_fmac_f32_e32 v42, 0x3377d1cf, v43
	v_fmac_f32_e32 v42, 0x3f317217, v43
	v_cmp_lt_f32_e64 s[22:23], |v43|, s70
	v_add_f32_e32 v32, 1.0, v32
	v_cndmask_b32_e32 v35, 0, v214, vcc
	v_cndmask_b32_e64 v34, v43, v42, s[22:23]
	v_cmp_gt_f32_e32 vcc, s1, v32
	v_sub_f32_e32 v34, v34, v35
	v_min_f32_e32 v41, 0, v41
	v_cndmask_b32_e64 v35, 0, 32, vcc
	v_ldexp_f32 v32, v32, v35
	v_log_f32_e32 v35, v32
	v_sub_f32_e32 v32, v41, v34
	v_mov_b32_e32 v85, v189
	v_cndmask_b32_e32 v39, 0, v214, vcc
	v_mul_f32_e32 v34, 0x3f317217, v35
	v_fma_f32 v34, v35, s74, -v34
	v_fmac_f32_e32 v34, 0x3377d1cf, v35
	v_fmac_f32_e32 v34, 0x3f317217, v35
	v_cmp_lt_f32_e64 s[22:23], |v35|, s70
	v_min_f32_e32 v33, 0, v33
	v_fma_f32 v64, v64, s75, 0
	v_cndmask_b32_e64 v38, v35, v34, s[22:23]
	s_waitcnt vmcnt(4)
; #define LAS __attribute__((address_space(3)))
; __device__ __forceinline__ float bf_lo(unsigned w) { return __uint_as_float(w << 16); }
; __device__ __forceinline__ float bf_hi(unsigned w) { return __uint_as_float(w & 0xffff0000u); }
; __device__ __forceinline__ float bf2f(bf16_t b) { return __uint_as_float(((unsigned)b) << 16); }
; template <bool OUT>
; __device__ __forceinline__ void gla_chunks(const Params& p, int l, const bf16_t* proj, LAS unsigned char* lds, int seg, int h, int dir, f32x4 (&Sacc)[4], float* outbuf, float& alog) {
;     ...
;           for (int j = 0; j < 8; ++j) { const u32x4 l0 = L0[j], l1 = L1[j]; float z = bias;
; #pragma unroll
;               for (int e = 0; e < 4; ++e) { z += bf_lo(l0[e]) * w[e * 2] + bf_hi(l0[e]) * w[e * 2 + 1]; z += bf_lo(l1[e]) * w[8 + e * 2] + bf_hi(l1[e]) * w[8 + e * 2 + 1]; }
;               const float ls = fminf(z, 0.f) - __logf(1.0f + __expf(-fabsf(z)));
;               run += ls * (1.0f / 16.0f); bq[j] = run;
;               kv[j] = bf2f(kr[j]);
;               if (OUT) qv[j] = bf2f(qr[j]) * 0.125f; }
;           PART[tb * 64 + d] = run; }
;         { const int pr = tid >> 4, part = tid & 15; const int i0 = 2 * pr, ta = dir ? t0 + 63 - i0 : t0 + i0, tbb = dir ? ta - 1 : ta + 1;
;           const u32x4 a = *(const u32x4*)(proj + (size_t)ta * NP + GV + h * 128 + part * 8), b = *(const u32x4*)(proj + (size_t)tbb * NP + GV + h * 128 + part * 8);
; #pragma unroll
;           for (int e = 0; e < 4; ++e) {
;               *(LAS unsigned*)(VT + (part * 8 + 2 * e) * GP + i0) = (a[e] & 0xffffu) | (b[e] << 16);
;               *(LAS unsigned*)(VT + (part * 8 + 2 * e + 1) * GP + i0) = (a[e] >> 16) | (b[e] & 0xffff0000u); } }
	v_lshlrev_b32_e32 v34, 16, v28
	v_and_b32_e32 v28, 0xffff0000, v28
	v_mul_f32_e32 v28, v87, v28
	v_fmac_f32_e32 v28, v95, v34
	v_lshlrev_b32_e32 v34, 16, v24
	v_and_b32_e32 v24, 0xffff0000, v24
	v_mul_f32_e32 v24, v92, v24
	v_add_f32_e32 v28, v86, v28
	v_fmac_f32_e32 v24, v91, v34
	v_add_f32_e32 v24, v24, v28
	v_lshlrev_b32_e32 v28, 16, v29
	v_and_b32_e32 v29, 0xffff0000, v29
	v_mul_f32_e32 v29, v89, v29
	v_fmac_f32_e32 v29, v88, v28
	v_lshlrev_b32_e32 v28, 16, v25
	v_and_b32_e32 v25, 0xffff0000, v25
	v_mul_f32_e32 v25, v94, v25
	v_add_f32_e32 v24, v29, v24
	v_fmac_f32_e32 v25, v93, v28
	v_and_b32_e32 v28, 0xffff0000, v30
	v_add_f32_e32 v24, v25, v24
	v_lshlrev_b32_e32 v25, 16, v30
	v_mul_f32_e32 v28, v96, v28
	v_fmac_f32_e32 v28, v90, v25
	v_lshlrev_b32_e32 v25, 16, v26
	v_and_b32_e32 v26, 0xffff0000, v26
	v_mul_f32_e32 v26, v100, v26
	v_add_f32_e32 v24, v28, v24
	v_fmac_f32_e32 v26, v99, v25
	v_add_f32_e32 v24, v26, v24
	v_and_b32_e32 v26, 0xffff0000, v31
	v_lshlrev_b32_e32 v25, 16, v31
	v_mul_f32_e32 v26, v98, v26
	v_fmac_f32_e32 v26, v97, v25
	v_add_f32_e32 v24, v26, v24
	v_and_b32_e32 v26, 0xffff0000, v27
	v_lshlrev_b32_e32 v25, 16, v27
	v_mul_f32_e32 v26, v102, v26
	v_fmac_f32_e32 v26, v101, v25
	v_add_f32_e32 v41, v26, v24
	v_mul_f32_e64 v24, |v41|, s60
	v_exp_f32_e32 v42, v24
	v_sub_u32_e32 v24, s48, v104
	v_add_u32_e32 v24, 63, v24
	v_add_u32_e32 v25, s48, v104
	v_cndmask_b32_e64 v26, v24, v25, s[4:5]
	v_mov_b64_e32 v[24:25], s[94:95]
	v_add_u32_e32 v28, s37, v26
	v_mad_i64_i32 v[26:27], s[22:23], v26, s63, v[24:25]
	v_lshl_add_u64 v[26:27], v[26:27], 0, s[90:91]
	v_lshl_add_u64 v[26:27], v[26:27], 0, v[84:85]
	v_mad_i64_i32 v[24:25], s[22:23], v28, s63, v[24:25]
	v_add_co_u32_e32 v26, vcc, s92, v26
	v_lshl_add_u64 v[24:25], v[24:25], 0, s[90:91]
	s_nop 0
	v_addc_co_u32_e32 v27, vcc, 0, v27, vcc
	v_lshl_add_u64 v[24:25], v[24:25], 0, v[84:85]
	v_add_co_u32_e32 v24, vcc, s92, v24
	v_fmamk_f32 v56, v56, 0x3d800000, v64
	s_nop 0
	v_addc_co_u32_e32 v25, vcc, 0, v25, vcc
	global_load_dwordx4 v[28:31], v[26:27], off offset:3584 nt
	global_load_dwordx4 v[34:37], v[24:25], off offset:3584 nt
	v_sub_f32_e32 v24, v38, v39
	v_sub_f32_e32 v24, v33, v24
	s_waitcnt vmcnt(3)
	v_lshlrev_b32_e32 v33, 16, v20
	v_and_b32_e32 v20, 0xffff0000, v20
	v_mul_f32_e32 v20, v87, v20
	v_fmac_f32_e32 v20, v95, v33
	v_lshlrev_b32_e32 v33, 16, v16
	v_and_b32_e32 v16, 0xffff0000, v16
	v_mul_f32_e32 v16, v92, v16
	v_add_f32_e32 v20, v86, v20
	v_fmac_f32_e32 v16, v91, v33
	v_add_f32_e32 v16, v16, v20
	v_lshlrev_b32_e32 v20, 16, v21
	v_and_b32_e32 v21, 0xffff0000, v21
	v_mul_f32_e32 v21, v89, v21
	v_fmac_f32_e32 v21, v88, v20
	v_lshlrev_b32_e32 v20, 16, v17
	v_and_b32_e32 v17, 0xffff0000, v17
	v_mul_f32_e32 v17, v94, v17
	v_add_f32_e32 v16, v21, v16
	v_fmac_f32_e32 v17, v93, v20
	v_and_b32_e32 v20, 0xffff0000, v22
	v_add_f32_e32 v16, v17, v16
	v_lshlrev_b32_e32 v17, 16, v22
	v_mul_f32_e32 v20, v96, v20
	v_fmac_f32_e32 v20, v90, v17
	v_lshlrev_b32_e32 v17, 16, v18
	v_and_b32_e32 v18, 0xffff0000, v18
	v_mul_f32_e32 v18, v100, v18
	v_add_f32_e32 v16, v20, v16
	v_fmac_f32_e32 v18, v99, v17
	v_add_f32_e32 v16, v18, v16
	v_and_b32_e32 v18, 0xffff0000, v23
	v_add_f32_e32 v25, 1.0, v42
	v_lshlrev_b32_e32 v17, 16, v23
	v_mul_f32_e32 v18, v98, v18
	v_cmp_gt_f32_e32 vcc, s1, v25
	v_fmac_f32_e32 v18, v97, v17
	v_add_f32_e32 v16, v18, v16
	v_cndmask_b32_e64 v26, 0, 32, vcc
	v_and_b32_e32 v18, 0xffff0000, v19
	v_ldexp_f32 v25, v25, v26
	v_lshlrev_b32_e32 v17, 16, v19
	v_mul_f32_e32 v18, v102, v18
	v_log_f32_e32 v25, v25
	v_fmac_f32_e32 v18, v101, v17
	v_add_f32_e32 v16, v18, v16
	v_mul_f32_e64 v17, |v16|, s60
	v_exp_f32_e32 v17, v17
	v_mul_f32_e32 v27, 0x3f317217, v25
	v_fma_f32 v27, v25, s74, -v27
	v_fmac_f32_e32 v27, 0x3377d1cf, v25
	v_fmac_f32_e32 v27, 0x3f317217, v25
	v_cmp_lt_f32_e64 s[22:23], |v25|, s70
	v_add_f32_e32 v17, 1.0, v17
	v_cndmask_b32_e32 v19, 0, v214, vcc
	v_cndmask_b32_e64 v18, v25, v27, s[22:23]
	v_cmp_gt_f32_e32 vcc, s1, v17
	v_sub_f32_e32 v18, v18, v19
	v_fmamk_f32 v48, v48, 0x3d800000, v56
	v_cndmask_b32_e64 v19, 0, 32, vcc
	v_ldexp_f32 v17, v17, v19
	v_log_f32_e32 v17, v17
	v_fmamk_f32 v40, v40, 0x3d800000, v48
	v_fmamk_f32 v32, v32, 0x3d800000, v40
	v_min_f32_e32 v26, 0, v41
	v_fmamk_f32 v24, v24, 0x3d800000, v32
	v_sub_f32_e32 v18, v26, v18
	v_fmamk_f32 v25, v18, 0x3d800000, v24
	v_mul_f32_e32 v18, 0x3f317217, v17
	v_fma_f32 v18, v17, s74, -v18
	v_fmac_f32_e32 v18, 0x3377d1cf, v17
	v_fmac_f32_e32 v18, 0x3f317217, v17
	v_cmp_lt_f32_e64 s[22:23], |v17|, s70
	v_min_f32_e32 v16, 0, v16
	s_nop 0
	v_cndmask_b32_e64 v17, v17, v18, s[22:23]
	v_cndmask_b32_e32 v18, 0, v214, vcc
	v_sub_f32_e32 v17, v17, v18
	v_sub_f32_e32 v16, v16, v17
	v_fmamk_f32 v26, v16, 0x3d800000, v25
	s_waitcnt vmcnt(1)
	v_and_b32_e32 v16, 0xffff, v28
	v_lshrrev_b32_e32 v17, 16, v28
	s_waitcnt vmcnt(0)
	s_sub_i32 s54, s48, s36
	s_add_i32 s54, s54, 63
	s_add_i32 s52, s48, s36
	s_and_b64 s[22:23], s[4:5], exec
	s_cselect_b32 s54, s52, s54
	s_cselect_b32 s53, 1, -1
	s_lshl_b32 s53, s53, 11
	s_lshl_b32 s54, s54, 11
	s_lshl_b32 s52, s47, 5
	s_add_i32 s54, s54, s52
	s_lshl_b32 s52, s28, 2
	s_add_i32 s54, s54, s52
	v_mov_b32_e32 v182, s53
	v_add_u32_e32 v180, s54, v105
	s_add_u32 s52, s94, 0x11000000
	s_addc_u32 s53, s95, 0
	global_store_dword v180, v64, s[52:53]
	v_add_u32_e32 v181, v180, v182
	global_store_dword v181, v56, s[52:53]
	v_add_u32_e32 v180, v181, v182
	global_store_dword v180, v48, s[52:53]
	v_add_u32_e32 v181, v180, v182
	global_store_dword v181, v40, s[52:53]
	v_add_u32_e32 v180, v181, v182
	global_store_dword v180, v32, s[52:53]
	v_add_u32_e32 v181, v180, v182
	global_store_dword v181, v24, s[52:53]
	v_add_u32_e32 v180, v181, v182
	global_store_dword v180, v25, s[52:53]
	v_add_u32_e32 v181, v180, v182
	global_store_dword v181, v26, s[52:53]
	v_lshl_or_b32 v16, v34, 16, v16
	v_and_or_b32 v17, v34, s0, v17
	v_add_u32_e32 v18, 0x6c00, v106
	ds_write2_b32 v18, v16, v17 offset1:36
	v_and_b32_e32 v16, 0xffff, v29
	v_lshrrev_b32_e32 v17, 16, v29
	v_lshl_or_b32 v16, v35, 16, v16
	v_and_or_b32 v17, v35, s0, v17
	ds_write2_b32 v18, v16, v17 offset0:72 offset1:108
	v_and_b32_e32 v16, 0xffff, v30
	v_lshrrev_b32_e32 v17, 16, v30
	v_lshl_or_b32 v16, v36, 16, v16
	v_and_or_b32 v17, v36, s0, v17
	ds_write2_b32 v18, v16, v17 offset0:144 offset1:180
	v_and_b32_e32 v16, 0xffff, v31
	v_lshrrev_b32_e32 v17, 16, v31
	v_lshl_or_b32 v16, v37, 16, v16
	v_and_or_b32 v17, v37, s0, v17
	ds_write_b32 v103, v26 offset:55552
	ds_write2_b32 v18, v16, v17 offset0:216 offset1:252
	s_waitcnt lgkmcnt(0)
	s_barrier
; template <bool OUT>
; __device__ __forceinline__ void gla_chunks(const Params& p, int l, const bf16_t* proj, LAS unsigned char* lds, int seg, int h, int dir, f32x4 (&Sacc)[4], float* outbuf, float& alog) {
;     ...
;         { float off = 0.f, tot = 0.f;
; #pragma unroll
;           for (int q = 0; q < 8; ++q) { const float v = PART[q * 64 + d]; tot += v; if (q < tb) off += v; }
;           if (tb == 0) { EBL[d] = __expf(tot); alog += tot; }
	ds_read2st64_b32 v[22:23], v105 offset0:217 offset1:218
	ds_read2st64_b32 v[20:21], v105 offset0:219 offset1:220
	ds_read2st64_b32 v[18:19], v105 offset0:221 offset1:222
	ds_read2st64_b32 v[16:17], v105 offset0:223 offset1:224
	s_andn2_b64 vcc, exec, s[24:25]
	s_waitcnt lgkmcnt(3)
	v_add_f32_e32 v27, 0, v22
	v_add_f32_e32 v22, v27, v23
	s_waitcnt lgkmcnt(2)
	v_add_f32_e32 v22, v22, v20
	v_add_f32_e32 v22, v22, v21
	s_waitcnt lgkmcnt(1)
	v_add_f32_e32 v22, v22, v18
	v_add_f32_e32 v22, v22, v19
	s_waitcnt lgkmcnt(0)
	v_add_f32_e32 v22, v22, v16
	v_add_f32_e32 v22, v22, v17
	s_cbranch_vccnz .LBB0_487
	v_mul_f32_e32 v28, 0x3fb8aa3b, v22
	v_exp_f32_e32 v28, v28
	v_add_f32_e32 v83, v83, v22
	ds_write_b32 v105, v28 offset:55296
	s_branch .LBB0_487
